# docs 7.3: prompt attention output rows stored as 4 dwordx4 per wave (v_permlane32_swap pairs) instead of 8 dwordx2
# speedup vs baseline: 1.0048x; 1.0028x over previous
; __device__ __forceinline__ int crow(int reg, int h) { return (reg & 3) + 8 * (reg >> 2) + 4 * h; }
; __device__ __forceinline__ void attn_prompt_wave(const Params& P, int l, int qt, int tid_in) {
;     ...
; #pragma unroll
;     for (int kb = 0; kb < 5; ++kb) {
;         if (kb >= 1 && kb <= 3 && interior) {
; #pragma unroll
;             for (int i = 0; i < 16; ++i) mx = fmaxf(mx, st[kb][i]);
;         } else {
; #pragma unroll
;             for (int i = 0; i < 16; ++i) { const int ki = key0 + kb * 32 + crow(i, h); const bool ok = ki <= qi && ki > qi - 128 && ki >= bstart;
;                 st[kb][i] = ok ? st[kb][i] : -1e30f; mx = fmaxf(mx, st[kb][i]); }
;         }
;     }
;     mx = fmaxf(mx, __shfl_xor(mx, 32));
;     float sum = 0.f;
; #pragma unroll
;     for (int kb = 0; kb < 5; ++kb)
; #pragma unroll
;         for (int i = 0; i < 16; ++i) { const float p = st[kb][i] > -1e29f ? __expf(st[kb][i] - mx) : 0.f; st[kb][i] = p; sum += p; }
;     sum += __shfl_xor(sum, 32);
;     const float inv = 1.f / (sum + __expf(sink - mx));
.LBB0_952:
	v_add_u32_e32 v56, 0x80, v183
	v_cmp_le_i32_e32 vcc, v56, v182
	v_cmp_gt_i32_e64 s[36:37], v56, v190
	s_and_b64 s[0:1], vcc, s[36:37]
	v_cmp_ge_i32_e32 vcc, v56, v185
	s_and_b64 vcc, s[0:1], vcc
	v_cmp_ge_i32_e64 s[36:37], v56, v190
	v_cndmask_b32_e32 v55, v233, v32, vcc
	v_or_b32_e32 v32, 1, v56
	v_cmp_ge_i32_e64 s[38:39], v32, v185
	v_cmp_lt_i32_e32 vcc, v56, v182
	s_and_b64 s[0:1], s[36:37], s[38:39]
	s_and_b64 vcc, s[0:1], vcc
	v_cndmask_b32_e32 v53, v233, v33, vcc
	v_or_b32_e32 v33, 2, v56
	v_cmp_le_i32_e32 vcc, v33, v182
	v_cmp_gt_i32_e64 s[36:37], v33, v190
	s_and_b64 s[0:1], vcc, s[36:37]
	v_cmp_ge_i32_e32 vcc, v33, v185
	s_and_b64 vcc, s[0:1], vcc
	v_or_b32_e32 v33, 3, v56
	v_cndmask_b32_e32 v54, v233, v34, vcc
	v_cmp_le_i32_e32 vcc, v33, v182
	v_cmp_gt_i32_e64 s[36:37], v33, v190
	s_and_b64 s[0:1], vcc, s[36:37]
	v_cmp_ge_i32_e32 vcc, v33, v185
	s_and_b64 vcc, s[0:1], vcc
	v_or_b32_e32 v33, 8, v56
	v_cndmask_b32_e32 v52, v233, v35, vcc
	v_cmp_le_i32_e32 vcc, v33, v182
	v_cmp_gt_i32_e64 s[36:37], v33, v190
	s_and_b64 s[0:1], vcc, s[36:37]
	v_cmp_ge_i32_e32 vcc, v33, v185
	s_and_b64 vcc, s[0:1], vcc
	v_or_b32_e32 v33, 9, v56
	v_cndmask_b32_e32 v50, v233, v36, vcc
	v_cmp_le_i32_e32 vcc, v33, v182
	v_cmp_gt_i32_e64 s[36:37], v33, v190
	s_and_b64 s[0:1], vcc, s[36:37]
	v_cmp_ge_i32_e32 vcc, v33, v185
	s_and_b64 vcc, s[0:1], vcc
	v_or_b32_e32 v33, 10, v56
	v_cndmask_b32_e32 v51, v233, v37, vcc
	v_cmp_le_i32_e32 vcc, v33, v182
	v_cmp_gt_i32_e64 s[36:37], v33, v190
	s_and_b64 s[0:1], vcc, s[36:37]
	v_cmp_ge_i32_e32 vcc, v33, v185
	s_and_b64 vcc, s[0:1], vcc
	v_or_b32_e32 v33, 11, v56
	v_cndmask_b32_e32 v48, v233, v38, vcc
	v_cmp_le_i32_e32 vcc, v33, v182
	v_cmp_gt_i32_e64 s[36:37], v33, v190
	s_and_b64 s[0:1], vcc, s[36:37]
	v_cmp_ge_i32_e32 vcc, v33, v185
	s_and_b64 vcc, s[0:1], vcc
	v_or_b32_e32 v33, 16, v56
	v_cndmask_b32_e32 v49, v233, v39, vcc
	v_cmp_le_i32_e32 vcc, v33, v182
	v_cmp_gt_i32_e64 s[36:37], v33, v190
	s_and_b64 s[0:1], vcc, s[36:37]
	v_cmp_ge_i32_e32 vcc, v33, v185
	s_and_b64 vcc, s[0:1], vcc
	v_or_b32_e32 v33, 17, v56
	v_cndmask_b32_e32 v40, v233, v40, vcc
	v_cmp_le_i32_e32 vcc, v33, v182
	v_cmp_gt_i32_e64 s[36:37], v33, v190
	s_and_b64 s[0:1], vcc, s[36:37]
	v_cmp_ge_i32_e32 vcc, v33, v185
	s_and_b64 vcc, s[0:1], vcc
	v_or_b32_e32 v33, 18, v56
	v_cndmask_b32_e32 v38, v233, v41, vcc
	v_cmp_le_i32_e32 vcc, v33, v182
	v_cmp_gt_i32_e64 s[36:37], v33, v190
	s_and_b64 s[0:1], vcc, s[36:37]
	v_cmp_ge_i32_e32 vcc, v33, v185
	s_and_b64 vcc, s[0:1], vcc
	v_or_b32_e32 v33, 19, v56
	v_cndmask_b32_e32 v39, v233, v42, vcc
	v_cmp_le_i32_e32 vcc, v33, v182
	v_cmp_gt_i32_e64 s[36:37], v33, v190
	s_and_b64 s[0:1], vcc, s[36:37]
	v_cmp_ge_i32_e32 vcc, v33, v185
	s_and_b64 vcc, s[0:1], vcc
	v_or_b32_e32 v33, 24, v56
	v_cndmask_b32_e32 v36, v233, v43, vcc
	v_cmp_le_i32_e32 vcc, v33, v182
	v_cmp_gt_i32_e64 s[36:37], v33, v190
	s_and_b64 s[0:1], vcc, s[36:37]
	v_cmp_ge_i32_e32 vcc, v33, v185
	s_and_b64 vcc, s[0:1], vcc
	v_or_b32_e32 v33, 25, v56
	v_cndmask_b32_e32 v37, v233, v44, vcc
	v_cmp_le_i32_e32 vcc, v33, v182
	v_cmp_gt_i32_e64 s[36:37], v33, v190
	s_and_b64 s[0:1], vcc, s[36:37]
	v_cmp_ge_i32_e32 vcc, v33, v185
	s_and_b64 vcc, s[0:1], vcc
	v_or_b32_e32 v33, 26, v56
	v_max3_f32 v32, v192, v55, v53
	v_cndmask_b32_e32 v35, v233, v45, vcc
	v_cmp_le_i32_e32 vcc, v33, v182
	v_cmp_gt_i32_e64 s[36:37], v33, v190
	v_max3_f32 v32, v32, v54, v52
	s_and_b64 s[0:1], vcc, s[36:37]
	v_cmp_ge_i32_e32 vcc, v33, v185
	v_max3_f32 v32, v32, v50, v51
	s_and_b64 vcc, s[0:1], vcc
	v_or_b32_e32 v34, 27, v56
	v_max3_f32 v32, v32, v48, v49
	v_cndmask_b32_e32 v33, v233, v46, vcc
	v_cmp_le_i32_e32 vcc, v34, v182
	v_cmp_gt_i32_e64 s[36:37], v34, v190
	v_max3_f32 v32, v32, v40, v38
	s_and_b64 s[0:1], vcc, s[36:37]
	v_cmp_ge_i32_e32 vcc, v34, v185
	v_max3_f32 v32, v32, v39, v36
	s_and_b64 vcc, s[0:1], vcc
	v_max3_f32 v32, v32, v37, v35
	v_cndmask_b32_e32 v34, v233, v47, vcc
	v_max3_f32 v32, v32, v33, v34
	v_mov_b32_e32 v41, v32
	s_nop 1
	v_permlane32_swap_b32 v32, v41
	v_cmp_lt_f32_e32 vcc, s35, v184
	v_lshlrev_b32_e32 v80, 1, v80
	s_waitcnt lgkmcnt(0)
	v_max_f32_e32 v41, v41, v41
	v_max_f32_e32 v32, v32, v41
	v_sub_f32_e32 v41, v184, v32
	v_mul_f32_e32 v41, 0x3fb8aa3b, v41
	v_sub_f32_e32 v42, v171, v32
	v_exp_f32_e32 v41, v41
	v_mul_f32_e32 v42, 0x3fb8aa3b, v42
	v_sub_f32_e32 v44, v177, v32
	v_exp_f32_e32 v42, v42
	v_mul_f32_e32 v44, 0x3fb8aa3b, v44
	v_exp_f32_e32 v44, v44
	v_cndmask_b32_e32 v41, 0, v41, vcc
	v_cmp_lt_f32_e32 vcc, s35, v171
	v_add_f32_e32 v43, 0, v41
	v_sub_f32_e32 v46, v176, v32
	v_cndmask_b32_e32 v42, 0, v42, vcc
	v_cmp_lt_f32_e32 vcc, s35, v177
	v_add_f32_e32 v45, v42, v43
	v_mul_f32_e32 v46, 0x3fb8aa3b, v46
	v_cndmask_b32_e32 v43, 0, v44, vcc
	v_sub_f32_e32 v44, v169, v32
	v_mul_f32_e32 v44, 0x3fb8aa3b, v44
	v_exp_f32_e32 v44, v44
	v_exp_f32_e32 v46, v46
	v_cmp_lt_f32_e32 vcc, s35, v169
	v_add_f32_e32 v45, v43, v45
	v_sub_f32_e32 v56, v175, v32
	v_cndmask_b32_e32 v44, 0, v44, vcc
	v_cmp_lt_f32_e32 vcc, s35, v176
	v_add_f32_e32 v47, v44, v45
	v_mul_f32_e32 v56, 0x3fb8aa3b, v56
	v_cndmask_b32_e32 v45, 0, v46, vcc
	v_add_f32_e32 v46, v45, v47
	v_sub_f32_e32 v47, v168, v32
	v_mul_f32_e32 v47, 0x3fb8aa3b, v47
	v_exp_f32_e32 v47, v47
	v_sub_f32_e32 v57, v167, v32
	v_exp_f32_e32 v56, v56
	v_mul_f32_e32 v57, 0x3fb8aa3b, v57
	v_sub_f32_e32 v58, v174, v32
	v_exp_f32_e32 v57, v57
	v_mul_f32_e32 v58, 0x3fb8aa3b, v58
	v_cmp_lt_f32_e32 vcc, s35, v168
	v_exp_f32_e32 v58, v58
	v_sub_f32_e32 v60, v173, v32
	v_cndmask_b32_e32 v47, 0, v47, vcc
	v_cmp_lt_f32_e32 vcc, s35, v175
	v_add_f32_e32 v46, v47, v46
	v_mul_f32_e32 v60, 0x3fb8aa3b, v60
; __device__ __forceinline__ void attn_prompt_wave(const Params& P, int l, int qt, int tid_in) {
;     ...
;     float sum = 0.f;
; #pragma unroll
;     for (int kb = 0; kb < 5; ++kb)
; #pragma unroll
;         for (int i = 0; i < 16; ++i) { const float p = st[kb][i] > -1e29f ? __expf(st[kb][i] - mx) : 0.f; st[kb][i] = p; sum += p; }
;     sum += __shfl_xor(sum, 32);
	v_cndmask_b32_e32 v56, 0, v56, vcc
	v_cmp_lt_f32_e32 vcc, s35, v167
	v_add_f32_e32 v46, v56, v46
	v_exp_f32_e32 v60, v60
	v_cndmask_b32_e32 v59, 0, v57, vcc
	v_cmp_lt_f32_e32 vcc, s35, v174
	v_add_f32_e32 v57, v59, v46
	v_sub_f32_e32 v62, v172, v32
	v_cndmask_b32_e32 v46, 0, v58, vcc
	v_add_f32_e32 v58, v46, v57
	v_sub_f32_e32 v57, v165, v32
	v_mul_f32_e32 v57, 0x3fb8aa3b, v57
	v_exp_f32_e32 v57, v57
	v_cmp_lt_f32_e32 vcc, s35, v165
	v_mul_f32_e32 v62, 0x3fb8aa3b, v62
	v_exp_f32_e32 v62, v62
	v_cndmask_b32_e32 v57, 0, v57, vcc
	v_cmp_lt_f32_e32 vcc, s35, v173
	v_add_f32_e32 v61, v57, v58
	v_sub_f32_e32 v165, v0, v32
	v_cndmask_b32_e32 v58, 0, v60, vcc
	v_sub_f32_e32 v60, v164, v32
	v_mul_f32_e32 v60, 0x3fb8aa3b, v60
	v_exp_f32_e32 v60, v60
	v_cmp_lt_f32_e32 vcc, s35, v164
	v_add_f32_e32 v61, v58, v61
	v_sub_f32_e32 v164, v170, v32
	v_cndmask_b32_e32 v60, 0, v60, vcc
	v_cmp_lt_f32_e32 vcc, s35, v172
	v_add_f32_e32 v63, v60, v61
	v_mul_f32_e32 v164, 0x3fb8aa3b, v164
	v_cndmask_b32_e32 v61, 0, v62, vcc
	v_add_f32_e32 v62, v61, v63
	v_sub_f32_e32 v63, v163, v32
	v_mul_f32_e32 v63, 0x3fb8aa3b, v63
	v_exp_f32_e32 v63, v63
	v_exp_f32_e32 v164, v164
	v_cmp_lt_f32_e32 vcc, s35, v163
	v_mul_f32_e32 v165, 0x3fb8aa3b, v165
	v_exp_f32_e32 v167, v165
	v_cndmask_b32_e32 v63, 0, v63, vcc
	v_cmp_lt_f32_e32 vcc, s35, v170
	v_add_f32_e32 v62, v63, v62
	s_nop 0
	v_cndmask_b32_e32 v163, 0, v164, vcc
	v_sub_f32_e32 v164, v162, v32
	v_mul_f32_e32 v164, 0x3fb8aa3b, v164
	v_exp_f32_e32 v164, v164
	v_cmp_lt_f32_e32 vcc, s35, v162
	v_add_f32_e32 v62, v163, v62
	s_nop 0
	v_cndmask_b32_e32 v165, 0, v164, vcc
	v_cmp_lt_f32_e32 vcc, s35, v0
	v_add_f32_e32 v162, v165, v62
	v_sub_f32_e32 v164, v2, v32
	v_cndmask_b32_e32 v62, 0, v167, vcc
	v_add_f32_e32 v0, v62, v162
	v_sub_f32_e32 v162, v1, v32
	v_mul_f32_e32 v162, 0x3fb8aa3b, v162
	v_exp_f32_e32 v162, v162
	v_mul_f32_e32 v164, 0x3fb8aa3b, v164
	v_cmp_lt_f32_e32 vcc, s35, v1
	v_sub_f32_e32 v1, v3, v32
	v_exp_f32_e32 v164, v164
	v_cndmask_b32_e32 v162, 0, v162, vcc
	v_cmp_lt_f32_e32 vcc, s35, v2
	v_mul_f32_e32 v1, 0x3fb8aa3b, v1
	v_sub_f32_e32 v2, v4, v32
	v_exp_f32_e32 v1, v1
	v_mul_f32_e32 v2, 0x3fb8aa3b, v2
	v_exp_f32_e32 v2, v2
	v_cndmask_b32_e32 v164, 0, v164, vcc
	v_cmp_lt_f32_e32 vcc, s35, v3
	v_add_f32_e32 v0, v162, v0
	v_add_f32_e32 v0, v164, v0
	v_cndmask_b32_e32 v167, 0, v1, vcc
	v_cmp_lt_f32_e32 vcc, s35, v4
	v_sub_f32_e32 v1, v5, v32
	v_mul_f32_e32 v1, 0x3fb8aa3b, v1
	v_cndmask_b32_e32 v168, 0, v2, vcc
	v_sub_f32_e32 v2, v6, v32
	v_exp_f32_e32 v1, v1
	v_mul_f32_e32 v2, 0x3fb8aa3b, v2
	v_exp_f32_e32 v2, v2
	v_cmp_lt_f32_e32 vcc, s35, v5
	v_add_f32_e32 v0, v167, v0
	v_add_f32_e32 v0, v168, v0
	v_cndmask_b32_e32 v169, 0, v1, vcc
	v_cmp_lt_f32_e32 vcc, s35, v6
	v_sub_f32_e32 v1, v7, v32
	v_mul_f32_e32 v1, 0x3fb8aa3b, v1
	v_cndmask_b32_e32 v170, 0, v2, vcc
	v_sub_f32_e32 v2, v8, v32
	v_exp_f32_e32 v1, v1
	v_mul_f32_e32 v2, 0x3fb8aa3b, v2
	v_exp_f32_e32 v2, v2
	v_cmp_lt_f32_e32 vcc, s35, v7
	v_add_f32_e32 v0, v169, v0
	v_add_f32_e32 v0, v170, v0
	v_cndmask_b32_e32 v171, 0, v1, vcc
	v_cmp_lt_f32_e32 vcc, s35, v8
	v_sub_f32_e32 v1, v9, v32
	v_mul_f32_e32 v1, 0x3fb8aa3b, v1
	v_cndmask_b32_e32 v172, 0, v2, vcc
	v_sub_f32_e32 v2, v10, v32
	v_exp_f32_e32 v1, v1
	v_mul_f32_e32 v2, 0x3fb8aa3b, v2
	v_exp_f32_e32 v2, v2
	v_cmp_lt_f32_e32 vcc, s35, v9
	v_add_f32_e32 v0, v171, v0
	v_add_f32_e32 v0, v172, v0
	v_cndmask_b32_e32 v173, 0, v1, vcc
	v_cmp_lt_f32_e32 vcc, s35, v10
	v_sub_f32_e32 v1, v11, v32
	v_mul_f32_e32 v1, 0x3fb8aa3b, v1
	v_cndmask_b32_e32 v174, 0, v2, vcc
	v_sub_f32_e32 v2, v12, v32
	v_exp_f32_e32 v1, v1
	v_mul_f32_e32 v2, 0x3fb8aa3b, v2
	v_exp_f32_e32 v2, v2
	v_cmp_lt_f32_e32 vcc, s35, v11
	v_add_f32_e32 v0, v173, v0
	v_add_f32_e32 v0, v174, v0
	v_cndmask_b32_e32 v175, 0, v1, vcc
	v_cmp_lt_f32_e32 vcc, s35, v12
	v_sub_f32_e32 v1, v13, v32
	v_mul_f32_e32 v1, 0x3fb8aa3b, v1
	v_cndmask_b32_e32 v176, 0, v2, vcc
	v_sub_f32_e32 v2, v14, v32
	v_exp_f32_e32 v1, v1
	v_mul_f32_e32 v2, 0x3fb8aa3b, v2
	v_exp_f32_e32 v2, v2
	v_cmp_lt_f32_e32 vcc, s35, v13
	v_add_f32_e32 v0, v175, v0
	v_add_f32_e32 v0, v176, v0
	v_cndmask_b32_e32 v177, 0, v1, vcc
	v_cmp_lt_f32_e32 vcc, s35, v14
	v_sub_f32_e32 v1, v15, v32
	v_mul_f32_e32 v1, 0x3fb8aa3b, v1
	v_cndmask_b32_e32 v182, 0, v2, vcc
	v_sub_f32_e32 v2, v16, v32
	v_exp_f32_e32 v1, v1
	v_mul_f32_e32 v2, 0x3fb8aa3b, v2
	v_exp_f32_e32 v2, v2
	v_cmp_lt_f32_e32 vcc, s35, v15
	v_add_f32_e32 v0, v177, v0
	v_add_f32_e32 v0, v182, v0
	v_cndmask_b32_e32 v183, 0, v1, vcc
	v_cmp_lt_f32_e32 vcc, s35, v16
	v_sub_f32_e32 v1, v17, v32
	v_mul_f32_e32 v1, 0x3fb8aa3b, v1
	v_cndmask_b32_e32 v184, 0, v2, vcc
	v_sub_f32_e32 v2, v18, v32
	v_exp_f32_e32 v1, v1
	v_mul_f32_e32 v2, 0x3fb8aa3b, v2
	v_exp_f32_e32 v2, v2
	v_cmp_lt_f32_e32 vcc, s35, v17
	v_add_f32_e32 v0, v183, v0
	v_add_f32_e32 v0, v184, v0
	v_cndmask_b32_e32 v185, 0, v1, vcc
	v_cmp_lt_f32_e32 vcc, s35, v18
	v_sub_f32_e32 v1, v19, v32
	v_mul_f32_e32 v1, 0x3fb8aa3b, v1
	v_cndmask_b32_e32 v186, 0, v2, vcc
	v_sub_f32_e32 v2, v20, v32
	v_exp_f32_e32 v1, v1
	v_mul_f32_e32 v2, 0x3fb8aa3b, v2
	v_exp_f32_e32 v2, v2
	v_cmp_lt_f32_e32 vcc, s35, v19
	v_add_f32_e32 v0, v185, v0
	v_add_f32_e32 v0, v186, v0
	v_cndmask_b32_e32 v187, 0, v1, vcc
	v_cmp_lt_f32_e32 vcc, s35, v20
	v_sub_f32_e32 v1, v21, v32
	v_mul_f32_e32 v1, 0x3fb8aa3b, v1
	v_cndmask_b32_e32 v188, 0, v2, vcc
	v_sub_f32_e32 v2, v22, v32
	v_exp_f32_e32 v1, v1
	v_mul_f32_e32 v2, 0x3fb8aa3b, v2
	v_exp_f32_e32 v2, v2
	v_cmp_lt_f32_e32 vcc, s35, v21
	v_add_f32_e32 v0, v187, v0
	v_add_f32_e32 v0, v188, v0
	v_cndmask_b32_e32 v189, 0, v1, vcc
	v_cmp_lt_f32_e32 vcc, s35, v22
	v_sub_f32_e32 v1, v23, v32
; __device__ __forceinline__ unsigned cvtpk(float lo, float hi) { f32x2_t v = {lo, hi}; bf16x2_t b = __builtin_convertvector(v, bf16x2_t); return __builtin_bit_cast(unsigned, b); }
; #define MFMA32(a, b, c) __builtin_amdgcn_mfma_f32_32x32x16_bf16((a), (b), (c), 0, 0, 0)
; __device__ __forceinline__ void attn_prompt_wave(const Params& P, int l, int qt, int tid_in) {
;     ...
;     for (int kb = 0; kb < 5; ++kb)
; #pragma unroll
;         for (int i = 0; i < 16; ++i) { const float p = st[kb][i] > -1e29f ? __expf(st[kb][i] - mx) : 0.f; st[kb][i] = p; sum += p; }
;     sum += __shfl_xor(sum, 32);
;     const float inv = 1.f / (sum + __expf(sink - mx));
;     f32x16 o0, o1;
; #pragma unroll
;     for (int i = 0; i < 16; ++i) { o0[i] = 0.f; o1[i] = 0.f; }
; #pragma unroll
;     for (int kb = 0; kb < 5; ++kb)
; #pragma unroll
;         for (int s = 0; s < 2; ++s) {
;             u32x4 pw; pw.x = cvtpk(st[kb][8 * s], st[kb][8 * s + 1]); pw.y = cvtpk(st[kb][8 * s + 2], st[kb][8 * s + 3]); pw.z = cvtpk(st[kb][8 * s + 4], st[kb][8 * s + 5]); pw.w = cvtpk(st[kb][8 * s + 6], st[kb][8 * s + 7]);
;             const bf16x8 pf = __builtin_bit_cast(bf16x8, pw);
; #pragma unroll
;             for (int db = 0; db < 2; ++db) {
;                 const u32x2 va = vfa[kb][s][db], vb = vfb[kb][s][db];
;                 u32x4 vw; vw.x = va.x; vw.y = va.y; vw.z = vb.x; vw.w = vb.y;
;                 const bf16x8 vf = __builtin_bit_cast(bf16x8, vw);
;                 if (db == 0) o0 = MFMA32(vf, pf, o0); else o1 = MFMA32(vf, pf, o1);
	v_mul_f32_e32 v1, 0x3fb8aa3b, v1
	v_cndmask_b32_e32 v190, 0, v2, vcc
	v_sub_f32_e32 v2, v24, v32
	v_exp_f32_e32 v1, v1
	v_mul_f32_e32 v2, 0x3fb8aa3b, v2
	v_exp_f32_e32 v2, v2
	v_cmp_lt_f32_e32 vcc, s35, v23
	v_add_f32_e32 v0, v189, v0
	v_add_f32_e32 v0, v190, v0
	v_cndmask_b32_e32 v191, 0, v1, vcc
	v_cmp_lt_f32_e32 vcc, s35, v24
	v_sub_f32_e32 v1, v25, v32
	v_mul_f32_e32 v1, 0x3fb8aa3b, v1
	v_cndmask_b32_e32 v192, 0, v2, vcc
	v_sub_f32_e32 v2, v26, v32
	v_exp_f32_e32 v1, v1
	v_mul_f32_e32 v2, 0x3fb8aa3b, v2
	v_exp_f32_e32 v2, v2
	v_cmp_lt_f32_e32 vcc, s35, v25
	v_add_f32_e32 v0, v191, v0
	v_add_f32_e32 v0, v192, v0
	v_cndmask_b32_e32 v193, 0, v1, vcc
	v_cmp_lt_f32_e32 vcc, s35, v26
	v_sub_f32_e32 v1, v27, v32
	v_mul_f32_e32 v1, 0x3fb8aa3b, v1
	v_cndmask_b32_e32 v194, 0, v2, vcc
	v_sub_f32_e32 v2, v28, v32
	v_exp_f32_e32 v1, v1
	v_mul_f32_e32 v2, 0x3fb8aa3b, v2
	v_exp_f32_e32 v2, v2
	v_cmp_lt_f32_e32 vcc, s35, v27
	v_add_f32_e32 v0, v193, v0
	v_add_f32_e32 v0, v194, v0
	v_cndmask_b32_e32 v195, 0, v1, vcc
	v_cmp_lt_f32_e32 vcc, s35, v28
	v_sub_f32_e32 v1, v29, v32
	v_mul_f32_e32 v1, 0x3fb8aa3b, v1
	v_cndmask_b32_e32 v196, 0, v2, vcc
	v_sub_f32_e32 v2, v30, v32
	v_exp_f32_e32 v1, v1
	v_mul_f32_e32 v2, 0x3fb8aa3b, v2
	v_exp_f32_e32 v2, v2
	v_cmp_lt_f32_e32 vcc, s35, v29
	v_add_f32_e32 v0, v195, v0
	v_add_f32_e32 v0, v196, v0
	v_cndmask_b32_e32 v197, 0, v1, vcc
	v_cmp_lt_f32_e32 vcc, s35, v30
	v_sub_f32_e32 v1, v31, v32
	v_mul_f32_e32 v1, 0x3fb8aa3b, v1
	v_cndmask_b32_e32 v198, 0, v2, vcc
	v_sub_f32_e32 v2, v69, v32
	v_exp_f32_e32 v1, v1
	v_mul_f32_e32 v2, 0x3fb8aa3b, v2
	v_exp_f32_e32 v2, v2
	v_cmp_lt_f32_e32 vcc, s35, v31
	v_add_f32_e32 v0, v197, v0
	v_add_f32_e32 v0, v198, v0
	v_cndmask_b32_e32 v199, 0, v1, vcc
	v_cmp_lt_f32_e32 vcc, s35, v69
	v_sub_f32_e32 v1, v64, v32
	v_mul_f32_e32 v1, 0x3fb8aa3b, v1
	v_cndmask_b32_e32 v69, 0, v2, vcc
	v_sub_f32_e32 v2, v71, v32
	v_exp_f32_e32 v1, v1
	v_mul_f32_e32 v2, 0x3fb8aa3b, v2
	v_exp_f32_e32 v2, v2
	v_cmp_lt_f32_e32 vcc, s35, v64
	v_add_f32_e32 v0, v199, v0
	v_add_f32_e32 v0, v69, v0
	v_cndmask_b32_e32 v64, 0, v1, vcc
	v_cmp_lt_f32_e32 vcc, s35, v71
	v_sub_f32_e32 v1, v65, v32
	v_mul_f32_e32 v1, 0x3fb8aa3b, v1
	v_cndmask_b32_e32 v71, 0, v2, vcc
	v_sub_f32_e32 v2, v73, v32
	v_exp_f32_e32 v1, v1
	v_mul_f32_e32 v2, 0x3fb8aa3b, v2
	v_exp_f32_e32 v2, v2
	v_cmp_lt_f32_e32 vcc, s35, v65
	v_add_f32_e32 v0, v64, v0
	v_add_f32_e32 v0, v71, v0
	v_cndmask_b32_e32 v65, 0, v1, vcc
	v_cmp_lt_f32_e32 vcc, s35, v73
	v_sub_f32_e32 v1, v66, v32
	v_mul_f32_e32 v1, 0x3fb8aa3b, v1
	v_cndmask_b32_e32 v73, 0, v2, vcc
	v_sub_f32_e32 v2, v75, v32
	v_exp_f32_e32 v1, v1
	v_mul_f32_e32 v2, 0x3fb8aa3b, v2
	v_exp_f32_e32 v2, v2
	v_cmp_lt_f32_e32 vcc, s35, v66
	v_add_f32_e32 v0, v65, v0
	v_add_f32_e32 v0, v73, v0
	v_cndmask_b32_e32 v66, 0, v1, vcc
	v_cmp_lt_f32_e32 vcc, s35, v75
	v_sub_f32_e32 v1, v67, v32
	v_mul_f32_e32 v1, 0x3fb8aa3b, v1
	v_cndmask_b32_e32 v75, 0, v2, vcc
	v_sub_f32_e32 v2, v76, v32
	v_exp_f32_e32 v1, v1
	v_mul_f32_e32 v2, 0x3fb8aa3b, v2
	v_exp_f32_e32 v2, v2
	v_cmp_lt_f32_e32 vcc, s35, v67
	v_add_f32_e32 v0, v66, v0
	v_add_f32_e32 v0, v75, v0
	v_cndmask_b32_e32 v67, 0, v1, vcc
	v_cmp_lt_f32_e32 vcc, s35, v76
	v_sub_f32_e32 v1, v68, v32
	v_mul_f32_e32 v1, 0x3fb8aa3b, v1
	v_cndmask_b32_e32 v76, 0, v2, vcc
	v_sub_f32_e32 v2, v77, v32
	v_exp_f32_e32 v1, v1
	v_mul_f32_e32 v2, 0x3fb8aa3b, v2
	v_exp_f32_e32 v2, v2
	v_cmp_lt_f32_e32 vcc, s35, v68
	v_add_f32_e32 v0, v67, v0
	v_add_f32_e32 v0, v76, v0
	v_cndmask_b32_e32 v68, 0, v1, vcc
	v_cmp_lt_f32_e32 vcc, s35, v77
	v_sub_f32_e32 v1, v70, v32
	v_mul_f32_e32 v1, 0x3fb8aa3b, v1
	v_cndmask_b32_e32 v77, 0, v2, vcc
	v_sub_f32_e32 v2, v78, v32
	v_exp_f32_e32 v1, v1
	v_mul_f32_e32 v2, 0x3fb8aa3b, v2
	v_exp_f32_e32 v2, v2
	v_cmp_lt_f32_e32 vcc, s35, v70
	v_add_f32_e32 v0, v68, v0
	v_add_f32_e32 v0, v77, v0
	v_cndmask_b32_e32 v70, 0, v1, vcc
	v_cmp_lt_f32_e32 vcc, s35, v78
	v_sub_f32_e32 v1, v72, v32
	v_mul_f32_e32 v1, 0x3fb8aa3b, v1
	v_cndmask_b32_e32 v78, 0, v2, vcc
	v_sub_f32_e32 v2, v79, v32
	v_exp_f32_e32 v1, v1
	v_mul_f32_e32 v2, 0x3fb8aa3b, v2
	v_exp_f32_e32 v2, v2
	v_cmp_lt_f32_e32 vcc, s35, v72
	v_add_f32_e32 v0, v70, v0
	v_add_f32_e32 v0, v78, v0
	v_cndmask_b32_e32 v72, 0, v1, vcc
	v_cmp_lt_f32_e32 vcc, s35, v79
	v_sub_f32_e32 v1, v74, v32
	v_mul_f32_e32 v1, 0x3fb8aa3b, v1
	v_cndmask_b32_e32 v79, 0, v2, vcc
	v_sub_f32_e32 v2, v55, v32
	v_exp_f32_e32 v1, v1
	v_mul_f32_e32 v2, 0x3fb8aa3b, v2
	v_exp_f32_e32 v2, v2
	v_add_f32_e32 v0, v72, v0
	v_cmp_lt_f32_e32 vcc, s35, v74
	v_add_f32_e32 v0, v79, v0
	v_sub_f32_e32 v22, v54, v32
	v_cndmask_b32_e32 v74, 0, v1, vcc
	v_cmp_lt_f32_e32 vcc, s35, v55
	v_add_f32_e32 v0, v74, v0
	v_mul_f32_e32 v22, 0x3fb8aa3b, v22
	v_cndmask_b32_e32 v55, 0, v2, vcc
	v_add_f32_e32 v20, v55, v0
	v_sub_f32_e32 v0, v53, v32
	v_mul_f32_e32 v0, 0x3fb8aa3b, v0
	v_exp_f32_e32 v21, v0
	v_exp_f32_e32 v22, v22
	v_cmp_lt_f32_e32 vcc, s35, v53
	v_cvt_pk_bf16_f32 v16, v41, v42
	v_cvt_pk_bf16_f32 v17, v43, v44
	v_cvt_pk_bf16_f32 v18, v45, v47
	v_cvt_pk_bf16_f32 v19, v56, v59
	v_cndmask_b32_e32 v47, 0, v21, vcc
	v_cmp_lt_f32_e32 vcc, s35, v54
	v_mfma_f32_32x32x16_bf16 v[0:15], v[86:89], v[16:19], 0
	v_add_f32_e32 v41, v47, v20
	v_cndmask_b32_e32 v53, 0, v22, vcc
	v_sub_f32_e32 v42, v52, v32
	v_mul_f32_e32 v42, 0x3fb8aa3b, v42
	v_exp_f32_e32 v54, v42
	v_cvt_pk_bf16_f32 v42, v46, v57
	v_cvt_pk_bf16_f32 v43, v58, v60
	v_mfma_f32_32x32x16_bf16 v[16:31], v[82:85], v[16:19], 0
	v_cvt_pk_bf16_f32 v44, v61, v63
	v_cvt_pk_bf16_f32 v45, v163, v165
	v_cmp_lt_f32_e32 vcc, s35, v52
	v_sub_f32_e32 v52, v50, v32
	v_mul_f32_e32 v52, 0x3fb8aa3b, v52
	v_cndmask_b32_e32 v46, 0, v54, vcc
; __device__ __forceinline__ unsigned cvtpk(float lo, float hi) { f32x2_t v = {lo, hi}; bf16x2_t b = __builtin_convertvector(v, bf16x2_t); return __builtin_bit_cast(unsigned, b); }
; #define MFMA32(a, b, c) __builtin_amdgcn_mfma_f32_32x32x16_bf16((a), (b), (c), 0, 0, 0)
; __device__ __forceinline__ void attn_prompt_wave(const Params& P, int l, int qt, int tid_in) {
;     ...
;     float sum = 0.f;
; #pragma unroll
;     for (int kb = 0; kb < 5; ++kb)
; #pragma unroll
;         for (int i = 0; i < 16; ++i) { const float p = st[kb][i] > -1e29f ? __expf(st[kb][i] - mx) : 0.f; st[kb][i] = p; sum += p; }
;     sum += __shfl_xor(sum, 32);
;     const float inv = 1.f / (sum + __expf(sink - mx));
;     f32x16 o0, o1;
; #pragma unroll
;     for (int i = 0; i < 16; ++i) { o0[i] = 0.f; o1[i] = 0.f; }
; #pragma unroll
;     for (int kb = 0; kb < 5; ++kb)
; #pragma unroll
;         for (int s = 0; s < 2; ++s) {
;             u32x4 pw; pw.x = cvtpk(st[kb][8 * s], st[kb][8 * s + 1]); pw.y = cvtpk(st[kb][8 * s + 2], st[kb][8 * s + 3]); pw.z = cvtpk(st[kb][8 * s + 4], st[kb][8 * s + 5]); pw.w = cvtpk(st[kb][8 * s + 6], st[kb][8 * s + 7]);
;             const bf16x8 pf = __builtin_bit_cast(bf16x8, pw);
; #pragma unroll
;             for (int db = 0; db < 2; ++db) {
;                 const u32x2 va = vfa[kb][s][db], vb = vfb[kb][s][db];
;                 u32x4 vw; vw.x = va.x; vw.y = va.y; vw.z = vb.x; vw.w = vb.y;
;                 const bf16x8 vf = __builtin_bit_cast(bf16x8, vw);
;                 if (db == 0) o0 = MFMA32(vf, pf, o0); else o1 = MFMA32(vf, pf, o1);
;             }
;         }
	v_exp_f32_e32 v52, v52
	v_mfma_f32_32x32x16_bf16 v[0:15], v[158:161], v[42:45], v[0:15]
	v_cmp_lt_f32_e32 vcc, s35, v50
	v_add_f32_e32 v41, v53, v41
	v_add_f32_e32 v41, v46, v41
	v_cndmask_b32_e32 v50, 0, v52, vcc
	v_sub_f32_e32 v52, v48, v32
	v_cmp_lt_f32_e32 vcc, s35, v51
	v_add_f32_e32 v41, v50, v41
	v_mfma_f32_32x32x16_bf16 v[16:31], v[154:157], v[42:45], v[16:31]
	v_sub_f32_e32 v42, v51, v32
	v_mul_f32_e32 v42, 0x3fb8aa3b, v42
	v_exp_f32_e32 v54, v42
	v_cvt_pk_bf16_f32 v42, v62, v162
	v_cvt_pk_bf16_f32 v43, v164, v167
	v_cvt_pk_bf16_f32 v44, v168, v169
	v_cvt_pk_bf16_f32 v45, v170, v171
	v_cndmask_b32_e32 v51, 0, v54, vcc
	v_sub_f32_e32 v54, v49, v32
	v_mfma_f32_32x32x16_bf16 v[0:15], v[150:153], v[42:45], v[0:15]
	v_mul_f32_e32 v54, 0x3fb8aa3b, v54
	v_cmp_lt_f32_e32 vcc, s35, v48
	v_exp_f32_e32 v54, v54
	v_add_f32_e32 v41, v51, v41
	v_mfma_f32_32x32x16_bf16 v[16:31], v[146:149], v[42:45], v[16:31]
	v_mul_f32_e32 v42, 0x3fb8aa3b, v52
	v_exp_f32_e32 v52, v42
	v_cvt_pk_bf16_f32 v42, v172, v173
	v_cvt_pk_bf16_f32 v43, v174, v175
	v_cvt_pk_bf16_f32 v44, v176, v177
	v_cvt_pk_bf16_f32 v45, v182, v183
	v_cndmask_b32_e32 v48, 0, v52, vcc
	v_cmp_lt_f32_e32 vcc, s35, v49
	v_mfma_f32_32x32x16_bf16 v[0:15], v[142:145], v[42:45], v[0:15]
	v_add_f32_e32 v41, v48, v41
	v_cndmask_b32_e32 v49, 0, v54, vcc
	v_cmp_lt_f32_e32 vcc, s35, v40
	v_add_f32_e32 v41, v49, v41
	v_mfma_f32_32x32x16_bf16 v[16:31], v[138:141], v[42:45], v[16:31]
	v_sub_f32_e32 v42, v40, v32
	v_mul_f32_e32 v42, 0x3fb8aa3b, v42
	v_exp_f32_e32 v52, v42
	v_cvt_pk_bf16_f32 v42, v184, v185
	v_cvt_pk_bf16_f32 v43, v186, v187
	v_cvt_pk_bf16_f32 v44, v188, v189
	v_cvt_pk_bf16_f32 v45, v190, v191
	v_sub_f32_e32 v40, v38, v32
	v_mul_f32_e32 v40, 0x3fb8aa3b, v40
	v_mfma_f32_32x32x16_bf16 v[0:15], v[134:137], v[42:45], v[0:15]
	v_exp_f32_e32 v56, v40
	v_sub_f32_e32 v40, v39, v32
	v_cndmask_b32_e32 v52, 0, v52, vcc
	v_mul_f32_e32 v40, 0x3fb8aa3b, v40
	v_add_f32_e32 v54, v52, v41
	v_cvt_pk_bf16_f32 v41, v194, v195
	v_cmp_lt_f32_e32 vcc, s35, v38
	v_mfma_f32_32x32x16_bf16 v[16:31], v[130:133], v[42:45], v[16:31]
	v_exp_f32_e32 v44, v40
	v_cvt_pk_bf16_f32 v40, v192, v193
	v_cvt_pk_bf16_f32 v42, v196, v197
	v_cvt_pk_bf16_f32 v43, v198, v199
	v_cndmask_b32_e32 v45, 0, v56, vcc
	v_cmp_lt_f32_e32 vcc, s35, v39
	v_add_f32_e32 v38, v45, v54
	v_mfma_f32_32x32x16_bf16 v[0:15], v[126:129], v[40:43], v[0:15]
	v_cndmask_b32_e32 v44, 0, v44, vcc
	v_add_f32_e32 v54, v44, v38
	v_sub_f32_e32 v38, v36, v32
	v_mul_f32_e32 v38, 0x3fb8aa3b, v38
	v_cvt_pk_bf16_f32 v39, v71, v65
	v_cmp_lt_f32_e32 vcc, s35, v36
	v_sub_f32_e32 v36, v35, v32
	v_mfma_f32_32x32x16_bf16 v[16:31], v[122:125], v[40:43], v[16:31]
	v_exp_f32_e32 v42, v38
	v_sub_f32_e32 v43, v37, v32
	v_cvt_pk_bf16_f32 v38, v69, v64
	v_cvt_pk_bf16_f32 v40, v73, v66
	v_cvt_pk_bf16_f32 v41, v75, v67
	v_mul_f32_e32 v43, 0x3fb8aa3b, v43
	v_exp_f32_e32 v43, v43
	v_mfma_f32_32x32x16_bf16 v[0:15], v[118:121], v[38:41], v[0:15]
	v_mul_f32_e32 v36, 0x3fb8aa3b, v36
	v_cndmask_b32_e32 v42, 0, v42, vcc
	v_cmp_lt_f32_e32 vcc, s35, v37
	v_add_f32_e32 v54, v42, v54
	v_cvt_pk_bf16_f32 v37, v77, v70
	v_cndmask_b32_e32 v43, 0, v43, vcc
	v_cmp_lt_f32_e32 vcc, s35, v35
	v_mfma_f32_32x32x16_bf16 v[16:31], v[114:117], v[38:41], v[16:31]
	v_exp_f32_e32 v40, v36
	v_add_f32_e32 v41, v43, v54
	v_cvt_pk_bf16_f32 v36, v76, v68
	v_cvt_pk_bf16_f32 v38, v78, v72
	v_cndmask_b32_e32 v40, 0, v40, vcc
	v_cvt_pk_bf16_f32 v39, v79, v74
	v_add_f32_e32 v35, v40, v41
	v_sub_f32_e32 v41, v33, v32
	v_mfma_f32_32x32x16_bf16 v[0:15], v[110:113], v[36:39], v[0:15]
	v_mul_f32_e32 v41, 0x3fb8aa3b, v41
	v_exp_f32_e32 v41, v41
	v_cmp_lt_f32_e32 vcc, s35, v33
	s_nop 1
	v_cndmask_b32_e32 v33, 0, v41, vcc
	v_cmp_lt_f32_e32 vcc, s35, v34
	v_mfma_f32_32x32x16_bf16 v[16:31], v[106:109], v[36:39], v[16:31]
	v_sub_f32_e32 v36, v34, v32
	v_mul_f32_e32 v36, 0x3fb8aa3b, v36
	v_exp_f32_e32 v54, v36
	v_add_f32_e32 v35, v33, v35
	v_cvt_pk_bf16_f32 v37, v53, v46
	v_cvt_pk_bf16_f32 v36, v55, v47
	v_cndmask_b32_e32 v41, 0, v54, vcc
	v_add_f32_e32 v46, v41, v35
	v_mov_b32_e32 v47, v46
	s_nop 1
	v_permlane32_swap_b32 v46, v47
	v_sub_f32_e32 v32, v166, v32
	v_mul_f32_e32 v32, 0x3fb8aa3b, v32
	v_exp_f32_e32 v32, v32
	v_cvt_pk_bf16_f32 v38, v50, v51
	v_cvt_pk_bf16_f32 v39, v48, v49
	v_cvt_pk_bf16_f32 v34, v52, v45
	v_cvt_pk_bf16_f32 v35, v44, v42
	v_mfma_f32_32x32x16_bf16 v[0:15], v[102:105], v[36:39], v[0:15]
	v_mfma_f32_32x32x16_bf16 v[16:31], v[98:101], v[36:39], v[16:31]
	v_cvt_pk_bf16_f32 v37, v33, v41
	s_waitcnt lgkmcnt(0)
; __device__ __forceinline__ unsigned cvtpk(float lo, float hi) { f32x2_t v = {lo, hi}; bf16x2_t b = __builtin_convertvector(v, bf16x2_t); return __builtin_bit_cast(unsigned, b); }
; #define MFMA32(a, b, c) __builtin_amdgcn_mfma_f32_32x32x16_bf16((a), (b), (c), 0, 0, 0)
; __device__ __forceinline__ void attn_prompt_wave(const Params& P, int l, int qt, int tid_in) {
;     ...
;     sum += __shfl_xor(sum, 32);
;     const float inv = 1.f / (sum + __expf(sink - mx));
;     f32x16 o0, o1;
; #pragma unroll
;     for (int i = 0; i < 16; ++i) { o0[i] = 0.f; o1[i] = 0.f; }
; #pragma unroll
;     for (int kb = 0; kb < 5; ++kb)
; #pragma unroll
;         for (int s = 0; s < 2; ++s) {
;             u32x4 pw; pw.x = cvtpk(st[kb][8 * s], st[kb][8 * s + 1]); pw.y = cvtpk(st[kb][8 * s + 2], st[kb][8 * s + 3]); pw.z = cvtpk(st[kb][8 * s + 4], st[kb][8 * s + 5]); pw.w = cvtpk(st[kb][8 * s + 6], st[kb][8 * s + 7]);
;             const bf16x8 pf = __builtin_bit_cast(bf16x8, pw);
; #pragma unroll
;             for (int db = 0; db < 2; ++db) {
;                 const u32x2 va = vfa[kb][s][db], vb = vfb[kb][s][db];
;                 u32x4 vw; vw.x = va.x; vw.y = va.y; vw.z = vb.x; vw.w = vb.y;
;                 const bf16x8 vf = __builtin_bit_cast(bf16x8, vw);
;                 if (db == 0) o0 = MFMA32(vf, pf, o0); else o1 = MFMA32(vf, pf, o1);
;             }
;         }
;     bf16* op = ATT + (size_t)qi * 512 + head * 64 + 4 * h;
; #pragma unroll
;     for (int g = 0; g < 4; ++g) {
;         u32x2 w; w.x = cvtpk(o0[4 * g] * inv, o0[4 * g + 1] * inv); w.y = cvtpk(o0[4 * g + 2] * inv, o0[4 * g + 3] * inv); *(u32x2*)(op + 8 * g) = w;
;         u32x2 w2; w2.x = cvtpk(o1[4 * g] * inv, o1[4 * g + 1] * inv); w2.y = cvtpk(o1[4 * g + 2] * inv, o1[4 * g + 3] * inv); *(u32x2*)(op + 32 + 8 * g) = w2;
;     }
	v_add_f32_e32 v33, v46, v47
	v_add_f32_e32 v32, v32, v33
	v_div_scale_f32 v33, s[0:1], v32, v32, 1.0
	v_rcp_f32_e32 v38, v33
	v_cvt_pk_bf16_f32 v36, v43, v40
	s_nop 1
	v_mfma_f32_32x32x16_bf16 v[0:15], v[94:97], v[34:37], v[0:15]
	v_mfma_f32_32x32x16_bf16 v[16:31], v[90:93], v[34:37], v[16:31]
	v_fma_f32 v34, -v33, v38, 1.0
	v_fmac_f32_e32 v38, v34, v38
	v_div_scale_f32 v34, vcc, 1.0, v32, 1.0
	v_mul_f32_e32 v35, v34, v38
	v_fma_f32 v36, -v33, v35, v34
	v_fmac_f32_e32 v35, v36, v38
	v_fma_f32 v33, -v33, v35, v34
	v_div_fmas_f32 v33, v33, v38, v35
	v_div_fixup_f32 v32, v33, v32, 1.0
	v_lshl_add_u64 v[34:35], s[86:87], 0, v[178:179]
	v_lshl_add_u64 v[34:35], v[180:181], 1, v[34:35]
	v_lshl_add_u64 v[34:35], v[80:81], 1, v[34:35]
	v_pk_mul_f32 v[36:37], v[0:1], v[32:33] op_sel_hi:[1,0]
	v_pk_mul_f32 v[38:39], v[2:3], v[32:33] op_sel_hi:[1,0]
	v_pk_mul_f32 v[40:41], v[4:5], v[32:33] op_sel_hi:[1,0]
	v_pk_mul_f32 v[42:43], v[6:7], v[32:33] op_sel_hi:[1,0]
	v_cvt_pk_bf16_f32 v36, v36, v37
	v_cvt_pk_bf16_f32 v37, v38, v39
	v_cvt_pk_bf16_f32 v38, v40, v41
	v_cvt_pk_bf16_f32 v39, v42, v43
	s_nop 1
	v_permlane32_swap_b32 v36, v38
	v_permlane32_swap_b32 v37, v39
	global_store_dwordx4 v[34:35], v[36:39], off
	s_nop 1
	v_pk_mul_f32 v[36:37], v[8:9], v[32:33] op_sel_hi:[1,0]
	v_pk_mul_f32 v[38:39], v[10:11], v[32:33] op_sel_hi:[1,0]
	v_pk_mul_f32 v[40:41], v[12:13], v[32:33] op_sel_hi:[1,0]
	v_pk_mul_f32 v[42:43], v[14:15], v[32:33] op_sel_hi:[1,0]
	v_cvt_pk_bf16_f32 v36, v36, v37
	v_cvt_pk_bf16_f32 v37, v38, v39
	v_cvt_pk_bf16_f32 v38, v40, v41
	v_cvt_pk_bf16_f32 v39, v42, v43
	s_nop 1
	v_permlane32_swap_b32 v36, v38
	v_permlane32_swap_b32 v37, v39
	global_store_dwordx4 v[34:35], v[36:39], off offset:32
	s_nop 1
	v_pk_mul_f32 v[36:37], v[16:17], v[32:33] op_sel_hi:[1,0]
	v_pk_mul_f32 v[38:39], v[18:19], v[32:33] op_sel_hi:[1,0]
	v_pk_mul_f32 v[40:41], v[20:21], v[32:33] op_sel_hi:[1,0]
	v_pk_mul_f32 v[42:43], v[22:23], v[32:33] op_sel_hi:[1,0]
	v_cvt_pk_bf16_f32 v36, v36, v37
	v_cvt_pk_bf16_f32 v37, v38, v39
	v_cvt_pk_bf16_f32 v38, v40, v41
	v_cvt_pk_bf16_f32 v39, v42, v43
	s_nop 1
	v_permlane32_swap_b32 v36, v38
	v_permlane32_swap_b32 v37, v39
	global_store_dwordx4 v[34:35], v[36:39], off offset:64
	s_nop 1
	v_pk_mul_f32 v[36:37], v[24:25], v[32:33] op_sel_hi:[1,0]
	v_pk_mul_f32 v[38:39], v[26:27], v[32:33] op_sel_hi:[1,0]
	v_pk_mul_f32 v[40:41], v[28:29], v[32:33] op_sel_hi:[1,0]
	v_pk_mul_f32 v[42:43], v[30:31], v[32:33] op_sel_hi:[1,0]
	v_cvt_pk_bf16_f32 v36, v36, v37
	v_cvt_pk_bf16_f32 v37, v38, v39
	v_cvt_pk_bf16_f32 v38, v40, v41
	v_cvt_pk_bf16_f32 v39, v42, v43
	s_nop 1
	v_permlane32_swap_b32 v36, v38
	v_permlane32_swap_b32 v37, v39
	global_store_dwordx4 v[34:35], v[36:39], off offset:96
	s_nop 1
